# prologue weight-transpose gain factors fetched with scalar loads (no vmcnt drain inside the item loop)
# baseline (speedup 1.0000x reference)
.LBB0_25:
	s_mul_hi_i32 s4, s44, 0x2aaaaaab
	s_lshr_b32 s5, s4, 31
	s_ashr_i32 s45, s4, 2
	s_mul_i32 s4, s40, 0x110
	v_add_u32_e32 v7, s4, v22
	ds_read_b32 v2, v7
	s_add_i32 s45, s45, s5
	s_lshl_b32 s44, s45, 6
	v_cndmask_b32_e64 v1, 0, 1, s[12:13]
	v_cmp_ne_u32_e64 s[4:5], 1, v1
	s_andn2_b64 vcc, exec, s[12:13]
	s_add_i32 s46, s44, s40
	s_cbranch_vccnz .LBB0_27
	s_ashr_i32 s47, s46, 31
	s_lshl_b64 s[50:51], s[46:47], 2
	s_add_u32 s50, s25, s50
	s_addc_u32 s51, s26, s51
	s_load_dword s100, s[50:51], 0x0
	s_waitcnt lgkmcnt(0)
	v_mul_f32_e32 v2, s100, v2
.LBB0_27:
	ds_read_b32 v1, v7 offset:272
	s_and_b64 vcc, exec, s[4:5]
	s_cbranch_vccnz .LBB0_29
	s_ashr_i32 s47, s46, 31
	s_lshl_b64 s[50:51], s[46:47], 2
	s_add_u32 s50, s25, s50
	s_addc_u32 s51, s26, s51
	s_load_dword s100, s[50:51], 0x4
	s_waitcnt lgkmcnt(0)
	v_mul_f32_e32 v1, s100, v1
.LBB0_29:
	ds_read_b32 v4, v7 offset:544
	s_and_b64 vcc, exec, s[4:5]
	s_cbranch_vccnz .LBB0_31
	s_ashr_i32 s47, s46, 31
	s_lshl_b64 s[50:51], s[46:47], 2
	s_add_u32 s50, s25, s50
	s_addc_u32 s51, s26, s51
	s_load_dword s100, s[50:51], 0x8
	s_waitcnt lgkmcnt(0)
	v_mul_f32_e32 v4, s100, v4
.LBB0_31:
	ds_read_b32 v3, v7 offset:816
	s_and_b64 vcc, exec, s[4:5]
	s_cbranch_vccnz .LBB0_33
	s_ashr_i32 s47, s46, 31
	s_lshl_b64 s[50:51], s[46:47], 2
	s_add_u32 s50, s25, s50
	s_addc_u32 s51, s26, s51
	s_load_dword s100, s[50:51], 0xc
	s_waitcnt lgkmcnt(0)
	v_mul_f32_e32 v3, s100, v3
.LBB0_33:
	ds_read_b32 v6, v7 offset:1088
	s_and_b64 vcc, exec, s[4:5]
	s_cbranch_vccnz .LBB0_35
	s_ashr_i32 s47, s46, 31
	s_lshl_b64 s[50:51], s[46:47], 2
	s_add_u32 s50, s25, s50
	s_addc_u32 s51, s26, s51
	s_load_dword s100, s[50:51], 0x10
	s_waitcnt lgkmcnt(0)
	v_mul_f32_e32 v6, s100, v6
.LBB0_35:
	ds_read_b32 v5, v7 offset:1360
	s_and_b64 vcc, exec, s[4:5]
	s_cbranch_vccnz .LBB0_37
	s_ashr_i32 s47, s46, 31
	s_lshl_b64 s[50:51], s[46:47], 2
	s_add_u32 s50, s25, s50
	s_addc_u32 s51, s26, s51
	s_load_dword s100, s[50:51], 0x14
	s_waitcnt lgkmcnt(0)
	v_mul_f32_e32 v5, s100, v5
.LBB0_37:
	ds_read_b32 v8, v7 offset:1632
	s_and_b64 vcc, exec, s[4:5]
	s_cbranch_vccnz .LBB0_39
	s_ashr_i32 s47, s46, 31
	s_lshl_b64 s[50:51], s[46:47], 2
	s_add_u32 s50, s25, s50
	s_addc_u32 s51, s26, s51
	s_load_dword s100, s[50:51], 0x18
	s_waitcnt lgkmcnt(0)
	v_mul_f32_e32 v8, s100, v8
.LBB0_39:
	v_add_u32_e32 v7, s27, v22
	ds_read_b32 v7, v7
	s_and_b64 vcc, exec, s[4:5]
	s_cbranch_vccnz .LBB0_20
	s_ashr_i32 s47, s46, 31
	s_lshl_b64 s[4:5], s[46:47], 2
	s_add_u32 s4, s25, s4
	s_addc_u32 s5, s26, s5
	s_load_dword s100, s[4:5], 0x1c
	s_waitcnt lgkmcnt(0)
	v_mul_f32_e32 v7, s100, v7
	s_branch .LBB0_20

.LBB0_53:
	s_mul_hi_i32 s4, s42, 0x4ec4ec4f
	s_lshr_b32 s5, s4, 31
	s_ashr_i32 s43, s4, 4
	s_mul_i32 s4, s36, 0x110
	v_add_u32_e32 v7, s4, v22
	ds_read_b32 v2, v7
	s_add_i32 s43, s43, s5
	s_lshl_b32 s42, s43, 6
	v_cndmask_b32_e64 v1, 0, 1, s[12:13]
	v_cmp_ne_u32_e64 s[4:5], 1, v1
	s_andn2_b64 vcc, exec, s[12:13]
	s_add_i32 s44, s42, s36
	s_cbranch_vccnz .LBB0_55
	s_ashr_i32 s45, s44, 31
	s_lshl_b64 s[48:49], s[44:45], 2
	s_add_u32 s48, s25, s48
	s_addc_u32 s49, s26, s49
	s_load_dword s100, s[48:49], 0x0
	s_waitcnt lgkmcnt(0)
	v_mul_f32_e32 v2, s100, v2
.LBB0_55:
	ds_read_b32 v1, v7 offset:272
	s_and_b64 vcc, exec, s[4:5]
	s_cbranch_vccnz .LBB0_57
	s_ashr_i32 s45, s44, 31
	s_lshl_b64 s[48:49], s[44:45], 2
	s_add_u32 s48, s25, s48
	s_addc_u32 s49, s26, s49
	s_load_dword s100, s[48:49], 0x4
	s_waitcnt lgkmcnt(0)
	v_mul_f32_e32 v1, s100, v1
.LBB0_57:
	ds_read_b32 v4, v7 offset:544
	s_and_b64 vcc, exec, s[4:5]
	s_cbranch_vccnz .LBB0_59
	s_ashr_i32 s45, s44, 31
	s_lshl_b64 s[48:49], s[44:45], 2
	s_add_u32 s48, s25, s48
	s_addc_u32 s49, s26, s49
	s_load_dword s100, s[48:49], 0x8
	s_waitcnt lgkmcnt(0)
	v_mul_f32_e32 v4, s100, v4
.LBB0_59:
	ds_read_b32 v3, v7 offset:816
	s_and_b64 vcc, exec, s[4:5]
	s_cbranch_vccnz .LBB0_61
	s_ashr_i32 s45, s44, 31
	s_lshl_b64 s[48:49], s[44:45], 2
	s_add_u32 s48, s25, s48
	s_addc_u32 s49, s26, s49
	s_load_dword s100, s[48:49], 0xc
	s_waitcnt lgkmcnt(0)
	v_mul_f32_e32 v3, s100, v3
.LBB0_61:
	ds_read_b32 v6, v7 offset:1088
	s_and_b64 vcc, exec, s[4:5]
	s_cbranch_vccnz .LBB0_63
	s_ashr_i32 s45, s44, 31
	s_lshl_b64 s[48:49], s[44:45], 2
	s_add_u32 s48, s25, s48
	s_addc_u32 s49, s26, s49
	s_load_dword s100, s[48:49], 0x10
	s_waitcnt lgkmcnt(0)
	v_mul_f32_e32 v6, s100, v6
.LBB0_63:
	ds_read_b32 v5, v7 offset:1360
	s_and_b64 vcc, exec, s[4:5]
	s_cbranch_vccnz .LBB0_65
	s_ashr_i32 s45, s44, 31
	s_lshl_b64 s[48:49], s[44:45], 2
	s_add_u32 s48, s25, s48
	s_addc_u32 s49, s26, s49
	s_load_dword s100, s[48:49], 0x14
	s_waitcnt lgkmcnt(0)
	v_mul_f32_e32 v5, s100, v5
.LBB0_65:
	ds_read_b32 v8, v7 offset:1632
	s_and_b64 vcc, exec, s[4:5]
	s_cbranch_vccnz .LBB0_67
	s_ashr_i32 s45, s44, 31
	s_lshl_b64 s[48:49], s[44:45], 2
	s_add_u32 s48, s25, s48
	s_addc_u32 s49, s26, s49
	s_load_dword s100, s[48:49], 0x18
	s_waitcnt lgkmcnt(0)
	v_mul_f32_e32 v8, s100, v8
.LBB0_67:
	v_add_u32_e32 v7, s27, v22
	ds_read_b32 v7, v7
	s_and_b64 vcc, exec, s[4:5]
	s_cbranch_vccnz .LBB0_48
	s_ashr_i32 s45, s44, 31
	s_lshl_b64 s[4:5], s[44:45], 2
	s_add_u32 s4, s25, s4
	s_addc_u32 s5, s26, s5
	s_load_dword s100, s[4:5], 0x1c
	s_waitcnt lgkmcnt(0)
	v_mul_f32_e32 v7, s100, v7
	s_branch .LBB0_48

.LBB0_79:
	s_mul_hi_i32 s4, s42, 0x2aaaaaab
	s_lshr_b32 s5, s4, 31
	s_ashr_i32 s43, s4, 3
	s_mul_i32 s4, s38, 0x110
	v_add_u32_e32 v7, s4, v22
	ds_read_b32 v2, v7
	s_add_i32 s43, s43, s5
	s_lshl_b32 s42, s43, 6
	v_cndmask_b32_e64 v1, 0, 1, s[12:13]
	v_cmp_ne_u32_e64 s[4:5], 1, v1
	s_andn2_b64 vcc, exec, s[12:13]
	s_add_i32 s44, s42, s38
	s_cbranch_vccnz .LBB0_81
	s_ashr_i32 s45, s44, 31
	s_lshl_b64 s[48:49], s[44:45], 2
	s_add_u32 s48, s25, s48
	s_addc_u32 s49, s26, s49
	s_load_dword s100, s[48:49], 0x0
	s_waitcnt lgkmcnt(0)
	v_mul_f32_e32 v2, s100, v2

.LBB0_120:
	s_ashr_i32 s8, s48, 31
	s_lshr_b32 s8, s8, 26
	s_add_i32 s49, s48, s8
	s_mul_i32 s8, s44, 0x110
	v_add_u32_e32 v7, s8, v22
	ds_read_b32 v2, v7
	s_and_b32 s48, s49, 0xffffffc0
	v_cndmask_b32_e64 v1, 0, 1, s[20:21]
	v_cmp_ne_u32_e64 s[8:9], 1, v1
	s_andn2_b64 vcc, exec, s[20:21]
	s_add_i32 s50, s48, s44
	s_cbranch_vccnz .LBB0_122
	s_ashr_i32 s51, s50, 31
	s_lshl_b64 s[76:77], s[50:51], 2
	s_add_u32 s76, s24, s76
	s_addc_u32 s77, s25, s77
	s_load_dword s100, s[76:77], 0x0
	s_waitcnt lgkmcnt(0)
	v_mul_f32_e32 v2, s100, v2
.LBB0_122:
	ds_read_b32 v1, v7 offset:272
	s_and_b64 vcc, exec, s[8:9]
	s_cbranch_vccnz .LBB0_124
	s_ashr_i32 s51, s50, 31
	s_lshl_b64 s[76:77], s[50:51], 2
	s_add_u32 s76, s24, s76
	s_addc_u32 s77, s25, s77
	s_load_dword s100, s[76:77], 0x4
	s_waitcnt lgkmcnt(0)
	v_mul_f32_e32 v1, s100, v1
.LBB0_124:
	ds_read_b32 v4, v7 offset:544
	s_and_b64 vcc, exec, s[8:9]
	s_cbranch_vccnz .LBB0_126
	s_ashr_i32 s51, s50, 31
	s_lshl_b64 s[76:77], s[50:51], 2
	s_add_u32 s76, s24, s76
	s_addc_u32 s77, s25, s77
	s_load_dword s100, s[76:77], 0x8
	s_waitcnt lgkmcnt(0)
	v_mul_f32_e32 v4, s100, v4
.LBB0_126:
	ds_read_b32 v3, v7 offset:816
	s_and_b64 vcc, exec, s[8:9]
	s_cbranch_vccnz .LBB0_128
	s_ashr_i32 s51, s50, 31
	s_lshl_b64 s[76:77], s[50:51], 2
	s_add_u32 s76, s24, s76
	s_addc_u32 s77, s25, s77
	s_load_dword s100, s[76:77], 0xc
	s_waitcnt lgkmcnt(0)
	v_mul_f32_e32 v3, s100, v3
.LBB0_128:
	ds_read_b32 v6, v7 offset:1088
	s_and_b64 vcc, exec, s[8:9]
	s_cbranch_vccnz .LBB0_130
	s_ashr_i32 s51, s50, 31
	s_lshl_b64 s[76:77], s[50:51], 2
	s_add_u32 s76, s24, s76
	s_addc_u32 s77, s25, s77
	s_load_dword s100, s[76:77], 0x10
	s_waitcnt lgkmcnt(0)
	v_mul_f32_e32 v6, s100, v6
.LBB0_130:
	ds_read_b32 v5, v7 offset:1360
	s_and_b64 vcc, exec, s[8:9]
	s_cbranch_vccnz .LBB0_132
	s_ashr_i32 s51, s50, 31
	s_lshl_b64 s[76:77], s[50:51], 2
	s_add_u32 s76, s24, s76
	s_addc_u32 s77, s25, s77
	s_load_dword s100, s[76:77], 0x14
	s_waitcnt lgkmcnt(0)
	v_mul_f32_e32 v5, s100, v5
.LBB0_132:
	ds_read_b32 v8, v7 offset:1632
	s_and_b64 vcc, exec, s[8:9]
	s_cbranch_vccnz .LBB0_134
	s_ashr_i32 s51, s50, 31
	s_lshl_b64 s[76:77], s[50:51], 2
	s_add_u32 s76, s24, s76
	s_addc_u32 s77, s25, s77
	s_load_dword s100, s[76:77], 0x18
	s_waitcnt lgkmcnt(0)
	v_mul_f32_e32 v8, s100, v8
.LBB0_134:
	v_add_u32_e32 v7, s26, v22
	ds_read_b32 v7, v7
	s_and_b64 vcc, exec, s[8:9]
	s_cbranch_vccnz .LBB0_115
	s_ashr_i32 s51, s50, 31
	s_lshl_b64 s[8:9], s[50:51], 2
	s_add_u32 s8, s24, s8
	s_addc_u32 s9, s25, s9
	s_load_dword s100, s[8:9], 0x1c
	s_waitcnt lgkmcnt(0)
	v_mul_f32_e32 v7, s100, v7
	s_branch .LBB0_115

.LBB0_163:
	s_ashr_i32 s4, s38, 31
	s_lshr_b32 s4, s4, 28
	s_add_i32 s4, s38, s4
	s_ashr_i32 s39, s4, 4
	s_mul_i32 s4, s34, 0x110
	v_add_u32_e32 v7, s4, v22
	ds_read_b32 v2, v7
	s_lshl_b32 s38, s39, 6
	v_cndmask_b32_e64 v1, 0, 1, s[28:29]
	v_cmp_ne_u32_e64 s[4:5], 1, v1
	s_andn2_b64 vcc, exec, s[28:29]
	s_add_i32 s40, s38, s34
	s_cbranch_vccnz .LBB0_165
	s_ashr_i32 s41, s40, 31
	s_lshl_b64 s[44:45], s[40:41], 2
	s_add_u32 s44, s24, s44
	s_addc_u32 s45, s25, s45
	s_load_dword s100, s[44:45], 0x0
	s_waitcnt lgkmcnt(0)
	v_mul_f32_e32 v2, s100, v2
.LBB0_165:
	ds_read_b32 v1, v7 offset:272
	s_and_b64 vcc, exec, s[4:5]
	s_cbranch_vccnz .LBB0_167
	s_ashr_i32 s41, s40, 31
	s_lshl_b64 s[44:45], s[40:41], 2
	s_add_u32 s44, s24, s44
	s_addc_u32 s45, s25, s45
	s_load_dword s100, s[44:45], 0x4
	s_waitcnt lgkmcnt(0)
	v_mul_f32_e32 v1, s100, v1
.LBB0_167:
	ds_read_b32 v4, v7 offset:544
	s_and_b64 vcc, exec, s[4:5]
	s_cbranch_vccnz .LBB0_169
	s_ashr_i32 s41, s40, 31
	s_lshl_b64 s[44:45], s[40:41], 2
	s_add_u32 s44, s24, s44
	s_addc_u32 s45, s25, s45
	s_load_dword s100, s[44:45], 0x8
	s_waitcnt lgkmcnt(0)
	v_mul_f32_e32 v4, s100, v4
.LBB0_169:
	ds_read_b32 v3, v7 offset:816
	s_and_b64 vcc, exec, s[4:5]
	s_cbranch_vccnz .LBB0_171
	s_ashr_i32 s41, s40, 31
	s_lshl_b64 s[44:45], s[40:41], 2
	s_add_u32 s44, s24, s44
	s_addc_u32 s45, s25, s45
	s_load_dword s100, s[44:45], 0xc
	s_waitcnt lgkmcnt(0)
	v_mul_f32_e32 v3, s100, v3
.LBB0_171:
	ds_read_b32 v6, v7 offset:1088
	s_and_b64 vcc, exec, s[4:5]
	s_cbranch_vccnz .LBB0_173
	s_ashr_i32 s41, s40, 31
	s_lshl_b64 s[44:45], s[40:41], 2
	s_add_u32 s44, s24, s44
	s_addc_u32 s45, s25, s45
	s_load_dword s100, s[44:45], 0x10
	s_waitcnt lgkmcnt(0)
	v_mul_f32_e32 v6, s100, v6
.LBB0_173:
	ds_read_b32 v5, v7 offset:1360
	s_and_b64 vcc, exec, s[4:5]
	s_cbranch_vccnz .LBB0_175
	s_ashr_i32 s41, s40, 31
	s_lshl_b64 s[44:45], s[40:41], 2
	s_add_u32 s44, s24, s44
	s_addc_u32 s45, s25, s45
	s_load_dword s100, s[44:45], 0x14
	s_waitcnt lgkmcnt(0)
	v_mul_f32_e32 v5, s100, v5
.LBB0_175:
	ds_read_b32 v8, v7 offset:1632
	s_and_b64 vcc, exec, s[4:5]
	s_cbranch_vccnz .LBB0_177
	s_ashr_i32 s41, s40, 31
	s_lshl_b64 s[44:45], s[40:41], 2
	s_add_u32 s44, s24, s44
	s_addc_u32 s45, s25, s45
	s_load_dword s100, s[44:45], 0x18
	s_waitcnt lgkmcnt(0)
	v_mul_f32_e32 v8, s100, v8
.LBB0_177:
	v_add_u32_e32 v7, s26, v22
	ds_read_b32 v7, v7
	s_and_b64 vcc, exec, s[4:5]
	s_cbranch_vccnz .LBB0_158
	s_ashr_i32 s41, s40, 31
	s_lshl_b64 s[4:5], s[40:41], 2
	s_add_u32 s4, s24, s4
	s_addc_u32 s5, s25, s5
	s_load_dword s100, s[4:5], 0x1c
	s_waitcnt lgkmcnt(0)
	v_mul_f32_e32 v7, s100, v7
	s_branch .LBB0_158

	.amdhsa_kernel _Z8mega_fwd4Args
		.amdhsa_group_segment_fixed_size 0
		.amdhsa_private_segment_fixed_size 0
		.amdhsa_kernarg_size 424
		.amdhsa_user_sgpr_count 2
		.amdhsa_user_sgpr_dispatch_ptr 0
		.amdhsa_user_sgpr_queue_ptr 0
		.amdhsa_user_sgpr_kernarg_segment_ptr 1
		.amdhsa_user_sgpr_dispatch_id 0
		.amdhsa_user_sgpr_kernarg_preload_length 0
		.amdhsa_user_sgpr_kernarg_preload_offset 0
		.amdhsa_user_sgpr_private_segment_size 0
		.amdhsa_uses_dynamic_stack 0
		.amdhsa_enable_private_segment 0
		.amdhsa_system_sgpr_workgroup_id_x 1
		.amdhsa_system_sgpr_workgroup_id_y 0
		.amdhsa_system_sgpr_workgroup_id_z 0
		.amdhsa_system_sgpr_workgroup_info 0
		.amdhsa_system_vgpr_workitem_id 2
		.amdhsa_next_free_vgpr 256
		.amdhsa_next_free_sgpr 102
		.amdhsa_accum_offset 256
		.amdhsa_reserve_vcc 1
		.amdhsa_float_round_mode_32 0
		.amdhsa_float_round_mode_16_64 0
		.amdhsa_float_denorm_mode_32 3
		.amdhsa_float_denorm_mode_16_64 3
		.amdhsa_dx10_clamp 1
		.amdhsa_ieee_mode 1
		.amdhsa_fp16_overflow 0
		.amdhsa_tg_split 0
		.amdhsa_exception_fp_ieee_invalid_op 0
		.amdhsa_exception_fp_denorm_src 0
		.amdhsa_exception_fp_ieee_div_zero 0
		.amdhsa_exception_fp_ieee_overflow 0
		.amdhsa_exception_fp_ieee_underflow 0
		.amdhsa_exception_fp_ieee_inexact 0
		.amdhsa_exception_int_div_zero 0
	.end_amdhsa_kernel

amdhsa.kernels:
  - .agpr_count:     0
    .args:
      - .offset:         0
        .size:           168
        .value_kind:     by_value
      - .offset:         168
        .size:           4
        .value_kind:     hidden_block_count_x
      - .offset:         172
        .size:           4
        .value_kind:     hidden_block_count_y
      - .offset:         176
        .size:           4
        .value_kind:     hidden_block_count_z
      - .offset:         180
        .size:           2
        .value_kind:     hidden_group_size_x
      - .offset:         182
        .size:           2
        .value_kind:     hidden_group_size_y
      - .offset:         184
        .size:           2
        .value_kind:     hidden_group_size_z
      - .offset:         186
        .size:           2
        .value_kind:     hidden_remainder_x
      - .offset:         188
        .size:           2
        .value_kind:     hidden_remainder_y
      - .offset:         190
        .size:           2
        .value_kind:     hidden_remainder_z
      - .offset:         208
        .size:           8
        .value_kind:     hidden_global_offset_x
      - .offset:         216
        .size:           8
        .value_kind:     hidden_global_offset_y
      - .offset:         224
        .size:           8
        .value_kind:     hidden_global_offset_z
      - .offset:         232
        .size:           2
        .value_kind:     hidden_grid_dims
      - .offset:         256
        .size:           8
        .value_kind:     hidden_multigrid_sync_arg
      - .offset:         288
        .size:           4
        .value_kind:     hidden_dynamic_lds_size
    .group_segment_fixed_size: 0
    .kernarg_segment_align: 8
    .kernarg_segment_size: 424
    .language:       OpenCL C
    .language_version:
      - 2
      - 0
    .max_flat_workgroup_size: 512
    .name:           _Z8mega_fwd4Args
    .private_segment_fixed_size: 0
    .sgpr_count:     108
    .sgpr_spill_count: 225
    .symbol:         _Z8mega_fwd4Args.kd
    .uniform_work_group_size: 1
    .uses_dynamic_stack: false
    .vgpr_count:     256
    .vgpr_spill_count: 0
    .wavefront_size: 64
